# GEMM K loops: each pre-barrier vmcnt(8) and lgkmcnt(0) pair merged into one s_waitcnt (12 sites)
# speedup vs baseline: 1.0011x; 1.0010x over previous
.LBB0_628:
	s_add_u32 s36, s30, 0xfffc0080
	s_addc_u32 s37, s31, -1
	s_add_i32 s53, 0, 0x10000
	s_cmp_eq_u32 s52, 12
	s_cselect_b32 s39, s15, s37
	s_cselect_b32 s38, s48, s36
	v_add_u32_e32 v145, s53, v141
	s_cselect_b32 s37, s13, s51
	s_cselect_b32 s36, s49, s50
	s_add_i32 s56, 0, 0x14000
	ds_read_b128 v[146:149], v145
	ds_read_b128 v[150:153], v145 offset:1024
	ds_read_b128 v[164:167], v145 offset:2048
	ds_read_b128 v[168:171], v145 offset:3072
	v_add_u32_e32 v145, s56, v141
	ds_read_b128 v[176:179], v145
	ds_read_b128 v[180:183], v145 offset:1024
	ds_read_b128 v[184:187], v145 offset:2048
	ds_read_b128 v[212:215], v145 offset:3072
	v_lshl_add_u64 v[154:155], s[30:31], 0, v[136:137]
	s_add_i32 m0, s41, 0xc000
	ds_read_b128 v[216:219], v144
	ds_read_b128 v[220:223], v144 offset:1024
	ds_read_b128 v[224:227], v144 offset:2048
	ds_read_b128 v[228:231], v144 offset:3072
	ds_read_b128 v[232:235], v144 offset:4096
	ds_read_b128 v[236:239], v144 offset:5120
	ds_read_b128 v[240:243], v144 offset:6144
	ds_read_b128 v[244:247], v144 offset:7168
	global_load_lds_dwordx4 v[154:155], off
	v_lshl_add_u64 v[154:155], s[30:31], 0, v[138:139]
	s_add_i32 m0, s41, 0xe000
	s_nop 0
	global_load_lds_dwordx4 v[154:155], off
	s_waitcnt vmcnt(8) lgkmcnt(0)
	s_barrier
	s_setprio 1
	s_waitcnt lgkmcnt(0)
	v_mfma_f32_16x16x32_bf16 v[126:129], v[146:149], v[216:219], v[126:129]
	v_mfma_f32_16x16x32_bf16 v[122:125], v[164:167], v[216:219], v[122:125]
	v_mfma_f32_16x16x32_bf16 v[118:121], v[146:149], v[224:227], v[118:121]
	v_mfma_f32_16x16x32_bf16 v[110:113], v[164:167], v[224:227], v[110:113]
	v_mfma_f32_16x16x32_bf16 v[98:101], v[146:149], v[232:235], v[98:101]
	v_mfma_f32_16x16x32_bf16 v[90:93], v[164:167], v[232:235], v[90:93]
	v_mfma_f32_16x16x32_bf16 v[86:89], v[146:149], v[240:243], v[86:89]
	v_mfma_f32_16x16x32_bf16 v[78:81], v[164:167], v[240:243], v[78:81]
	v_mfma_f32_16x16x32_bf16 v[126:129], v[150:153], v[220:223], v[126:129]
	v_mfma_f32_16x16x32_bf16 v[122:125], v[168:171], v[220:223], v[122:125]
	v_mfma_f32_16x16x32_bf16 v[118:121], v[150:153], v[228:231], v[118:121]
	v_mfma_f32_16x16x32_bf16 v[110:113], v[168:171], v[228:231], v[110:113]
	v_mfma_f32_16x16x32_bf16 v[98:101], v[150:153], v[236:239], v[98:101]
	v_mfma_f32_16x16x32_bf16 v[90:93], v[168:171], v[236:239], v[90:93]
	v_mfma_f32_16x16x32_bf16 v[86:89], v[150:153], v[244:247], v[86:89]
	v_mfma_f32_16x16x32_bf16 v[78:81], v[168:171], v[244:247], v[78:81]
	s_setprio 0
	s_setprio 1
	v_mfma_f32_16x16x32_bf16 v[114:117], v[176:179], v[216:219], v[114:117]
	v_mfma_f32_16x16x32_bf16 v[106:109], v[184:187], v[216:219], v[106:109]
	v_mfma_f32_16x16x32_bf16 v[102:105], v[176:179], v[224:227], v[102:105]
	v_mfma_f32_16x16x32_bf16 v[94:97], v[184:187], v[224:227], v[94:97]
	v_mfma_f32_16x16x32_bf16 v[82:85], v[176:179], v[232:235], v[82:85]
	v_mfma_f32_16x16x32_bf16 v[74:77], v[184:187], v[232:235], v[74:77]
	v_mfma_f32_16x16x32_bf16 v[70:73], v[176:179], v[240:243], v[70:73]
	v_mfma_f32_16x16x32_bf16 v[66:69], v[184:187], v[240:243], v[66:69]
	v_mfma_f32_16x16x32_bf16 v[114:117], v[180:183], v[220:223], v[114:117]
	v_mfma_f32_16x16x32_bf16 v[106:109], v[212:215], v[220:223], v[106:109]
	v_mfma_f32_16x16x32_bf16 v[102:105], v[180:183], v[228:231], v[102:105]
	v_mfma_f32_16x16x32_bf16 v[94:97], v[212:215], v[228:231], v[94:97]
	v_mfma_f32_16x16x32_bf16 v[82:85], v[180:183], v[236:239], v[82:85]
	v_mfma_f32_16x16x32_bf16 v[74:77], v[212:215], v[236:239], v[74:77]
	v_mfma_f32_16x16x32_bf16 v[70:73], v[180:183], v[244:247], v[70:73]
	v_mfma_f32_16x16x32_bf16 v[66:69], v[212:215], v[244:247], v[66:69]
	s_setprio 0
	s_barrier
	s_add_i32 s53, s53, s40
	v_lshl_add_u64 v[154:155], s[36:37], 0, v[0:1]
	s_mov_b32 m0, s53
	ds_read_b128 v[216:219], v144 offset:16384
	ds_read_b128 v[220:223], v144 offset:17408
	ds_read_b128 v[224:227], v144 offset:18432
	ds_read_b128 v[228:231], v144 offset:19456
	ds_read_b128 v[232:235], v144 offset:20480
	ds_read_b128 v[236:239], v144 offset:21504
	ds_read_b128 v[240:243], v144 offset:22528
	ds_read_b128 v[244:247], v144 offset:23552
	global_load_lds_dwordx4 v[154:155], off
	s_add_i32 m0, s53, 0x2000
	s_add_u32 s54, s36, 0x40000
	v_lshl_add_u64 v[172:173], s[36:37], 0, v[134:135]
	s_addc_u32 s55, s37, 0
	s_add_i32 s53, s56, s40
	global_load_lds_dwordx4 v[172:173], off
	v_lshl_add_u64 v[198:199], s[54:55], 0, v[0:1]
	s_mov_b32 m0, s53
	v_lshl_add_u64 v[248:249], s[38:39], 0, v[132:133]
	global_load_lds_dwordx4 v[198:199], off
	v_lshl_add_u64 v[198:199], s[54:55], 0, v[134:135]
	s_add_i32 m0, s53, 0x2000
	s_nop 0
	global_load_lds_dwordx4 v[198:199], off
	v_lshl_add_u64 v[198:199], s[38:39], 0, v[130:131]
	s_mov_b32 m0, s41
	s_nop 0
	global_load_lds_dwordx4 v[198:199], off
	s_mov_b32 m0, s42
	s_nop 0
	global_load_lds_dwordx4 v[248:249], off
	s_waitcnt vmcnt(8) lgkmcnt(0)
	s_barrier
	s_setprio 1
	s_waitcnt lgkmcnt(0)
	v_mfma_f32_16x16x32_bf16 v[62:65], v[146:149], v[216:219], v[62:65]
	v_mfma_f32_16x16x32_bf16 v[58:61], v[164:167], v[216:219], v[58:61]
	v_mfma_f32_16x16x32_bf16 v[54:57], v[146:149], v[224:227], v[54:57]
	v_mfma_f32_16x16x32_bf16 v[46:49], v[164:167], v[224:227], v[46:49]
	v_mfma_f32_16x16x32_bf16 v[34:37], v[146:149], v[232:235], v[34:37]
	v_mfma_f32_16x16x32_bf16 v[26:29], v[164:167], v[232:235], v[26:29]
	v_mfma_f32_16x16x32_bf16 v[22:25], v[146:149], v[240:243], v[22:25]
	v_mfma_f32_16x16x32_bf16 v[14:17], v[164:167], v[240:243], v[14:17]
	v_mfma_f32_16x16x32_bf16 v[62:65], v[150:153], v[220:223], v[62:65]
	v_mfma_f32_16x16x32_bf16 v[58:61], v[168:171], v[220:223], v[58:61]
	v_mfma_f32_16x16x32_bf16 v[54:57], v[150:153], v[228:231], v[54:57]
	v_mfma_f32_16x16x32_bf16 v[46:49], v[168:171], v[228:231], v[46:49]
	v_mfma_f32_16x16x32_bf16 v[34:37], v[150:153], v[236:239], v[34:37]
	v_mfma_f32_16x16x32_bf16 v[26:29], v[168:171], v[236:239], v[26:29]
	v_mfma_f32_16x16x32_bf16 v[22:25], v[150:153], v[244:247], v[22:25]
	v_mfma_f32_16x16x32_bf16 v[14:17], v[168:171], v[244:247], v[14:17]
	s_setprio 0
	s_setprio 1
	v_mfma_f32_16x16x32_bf16 v[50:53], v[176:179], v[216:219], v[50:53]
	v_mfma_f32_16x16x32_bf16 v[42:45], v[184:187], v[216:219], v[42:45]
	v_mfma_f32_16x16x32_bf16 v[38:41], v[176:179], v[224:227], v[38:41]
	v_mfma_f32_16x16x32_bf16 v[30:33], v[184:187], v[224:227], v[30:33]
	v_mfma_f32_16x16x32_bf16 v[18:21], v[176:179], v[232:235], v[18:21]
	v_mfma_f32_16x16x32_bf16 v[10:13], v[184:187], v[232:235], v[10:13]
	v_mfma_f32_16x16x32_bf16 v[6:9], v[176:179], v[240:243], v[6:9]
	v_mfma_f32_16x16x32_bf16 v[2:5], v[184:187], v[240:243], v[2:5]
	v_mfma_f32_16x16x32_bf16 v[50:53], v[180:183], v[220:223], v[50:53]
	v_mfma_f32_16x16x32_bf16 v[42:45], v[212:215], v[220:223], v[42:45]
	v_mfma_f32_16x16x32_bf16 v[38:41], v[180:183], v[228:231], v[38:41]
	v_mfma_f32_16x16x32_bf16 v[30:33], v[212:215], v[228:231], v[30:33]
	v_mfma_f32_16x16x32_bf16 v[18:21], v[180:183], v[236:239], v[18:21]
	v_mfma_f32_16x16x32_bf16 v[10:13], v[212:215], v[236:239], v[10:13]
	v_mfma_f32_16x16x32_bf16 v[6:9], v[180:183], v[244:247], v[6:9]
	v_mfma_f32_16x16x32_bf16 v[2:5], v[212:215], v[244:247], v[2:5]
	s_setprio 0
	s_barrier
	s_add_i32 s53, 0, 0x18000
	v_add_u32_e32 v145, s53, v141
	s_add_i32 s54, 0, 0x1c000
	ds_read_b128 v[146:149], v145
	ds_read_b128 v[150:153], v145 offset:1024
	ds_read_b128 v[164:167], v145 offset:2048
	ds_read_b128 v[168:171], v145 offset:3072
	v_add_u32_e32 v145, s54, v141
	ds_read_b128 v[176:179], v145
	ds_read_b128 v[180:183], v145 offset:1024
	ds_read_b128 v[184:187], v145 offset:2048
	ds_read_b128 v[212:215], v145 offset:3072
	s_add_u32 s38, s38, 0x40000
	s_addc_u32 s39, s39, 0
	s_mov_b32 m0, s43
	v_lshl_add_u64 v[250:251], s[38:39], 0, v[130:131]
	ds_read_b128 v[216:219], v144 offset:32768
	ds_read_b128 v[220:223], v144 offset:33792
	ds_read_b128 v[224:227], v144 offset:34816
	ds_read_b128 v[228:231], v144 offset:35840
	ds_read_b128 v[232:235], v144 offset:36864
	ds_read_b128 v[236:239], v144 offset:37888
	ds_read_b128 v[240:243], v144 offset:38912
	ds_read_b128 v[244:247], v144 offset:39936
	global_load_lds_dwordx4 v[250:251], off
	v_lshl_add_u64 v[250:251], s[38:39], 0, v[132:133]
	s_mov_b32 m0, s44
	s_nop 0
	global_load_lds_dwordx4 v[250:251], off
	s_waitcnt vmcnt(8) lgkmcnt(0)
	s_barrier
	s_setprio 1
	s_waitcnt lgkmcnt(0)
	v_mfma_f32_16x16x32_bf16 v[126:129], v[146:149], v[216:219], v[126:129]
	v_mfma_f32_16x16x32_bf16 v[122:125], v[164:167], v[216:219], v[122:125]
	v_mfma_f32_16x16x32_bf16 v[118:121], v[146:149], v[224:227], v[118:121]
	v_mfma_f32_16x16x32_bf16 v[110:113], v[164:167], v[224:227], v[110:113]
	v_mfma_f32_16x16x32_bf16 v[98:101], v[146:149], v[232:235], v[98:101]
	v_mfma_f32_16x16x32_bf16 v[90:93], v[164:167], v[232:235], v[90:93]
	v_mfma_f32_16x16x32_bf16 v[86:89], v[146:149], v[240:243], v[86:89]
	v_mfma_f32_16x16x32_bf16 v[78:81], v[164:167], v[240:243], v[78:81]
	v_mfma_f32_16x16x32_bf16 v[126:129], v[150:153], v[220:223], v[126:129]
	v_mfma_f32_16x16x32_bf16 v[122:125], v[168:171], v[220:223], v[122:125]
	v_mfma_f32_16x16x32_bf16 v[118:121], v[150:153], v[228:231], v[118:121]
	v_mfma_f32_16x16x32_bf16 v[110:113], v[168:171], v[228:231], v[110:113]
	v_mfma_f32_16x16x32_bf16 v[98:101], v[150:153], v[236:239], v[98:101]
	v_mfma_f32_16x16x32_bf16 v[90:93], v[168:171], v[236:239], v[90:93]
	v_mfma_f32_16x16x32_bf16 v[86:89], v[150:153], v[244:247], v[86:89]
	v_mfma_f32_16x16x32_bf16 v[78:81], v[168:171], v[244:247], v[78:81]
	s_setprio 0
	s_setprio 1
	v_mfma_f32_16x16x32_bf16 v[114:117], v[176:179], v[216:219], v[114:117]
	v_mfma_f32_16x16x32_bf16 v[106:109], v[184:187], v[216:219], v[106:109]
	v_mfma_f32_16x16x32_bf16 v[102:105], v[176:179], v[224:227], v[102:105]
	v_mfma_f32_16x16x32_bf16 v[94:97], v[184:187], v[224:227], v[94:97]
	v_mfma_f32_16x16x32_bf16 v[82:85], v[176:179], v[232:235], v[82:85]
	v_mfma_f32_16x16x32_bf16 v[74:77], v[184:187], v[232:235], v[74:77]
	v_mfma_f32_16x16x32_bf16 v[70:73], v[176:179], v[240:243], v[70:73]
	v_mfma_f32_16x16x32_bf16 v[66:69], v[184:187], v[240:243], v[66:69]
	v_mfma_f32_16x16x32_bf16 v[114:117], v[180:183], v[220:223], v[114:117]
	v_mfma_f32_16x16x32_bf16 v[106:109], v[212:215], v[220:223], v[106:109]
	v_mfma_f32_16x16x32_bf16 v[102:105], v[180:183], v[228:231], v[102:105]
	v_mfma_f32_16x16x32_bf16 v[94:97], v[212:215], v[228:231], v[94:97]
	v_mfma_f32_16x16x32_bf16 v[82:85], v[180:183], v[236:239], v[82:85]
	v_mfma_f32_16x16x32_bf16 v[74:77], v[212:215], v[236:239], v[74:77]
	v_mfma_f32_16x16x32_bf16 v[70:73], v[180:183], v[244:247], v[70:73]
	v_mfma_f32_16x16x32_bf16 v[66:69], v[212:215], v[244:247], v[66:69]
	s_setprio 0
	s_barrier
	s_add_i32 s38, s53, s40
	v_lshl_add_u64 v[154:155], v[154:155], 0, s[20:21]
	s_mov_b32 m0, s38
	ds_read_b128 v[216:219], v144 offset:49152
	ds_read_b128 v[220:223], v144 offset:50176
	ds_read_b128 v[224:227], v144 offset:51200
	ds_read_b128 v[228:231], v144 offset:52224
	ds_read_b128 v[232:235], v144 offset:53248
	ds_read_b128 v[236:239], v144 offset:54272
	ds_read_b128 v[240:243], v144 offset:55296
	ds_read_b128 v[244:247], v144 offset:56320
	global_load_lds_dwordx4 v[154:155], off
	s_add_i32 m0, s38, 0x2000
	s_add_u32 s36, s36, 0x40080
	v_lshl_add_u64 v[154:155], v[172:173], 0, s[20:21]
	s_addc_u32 s37, s37, 0
	s_add_i32 s38, s54, s40
	global_load_lds_dwordx4 v[154:155], off
	v_lshl_add_u64 v[154:155], s[36:37], 0, v[0:1]
	s_mov_b32 m0, s38
	s_nop 0
	global_load_lds_dwordx4 v[154:155], off
	v_lshl_add_u64 v[154:155], s[36:37], 0, v[134:135]
	s_add_i32 m0, s38, 0x2000
	s_nop 0
	global_load_lds_dwordx4 v[154:155], off
	v_lshl_add_u64 v[154:155], v[198:199], 0, s[20:21]
	s_mov_b32 m0, s45
	s_nop 0
	global_load_lds_dwordx4 v[154:155], off
	v_lshl_add_u64 v[154:155], v[248:249], 0, s[20:21]
	s_mov_b32 m0, s46
	s_nop 0
	global_load_lds_dwordx4 v[154:155], off
	s_waitcnt vmcnt(8) lgkmcnt(0)
	s_barrier
	s_setprio 1
	s_waitcnt lgkmcnt(0)
	v_mfma_f32_16x16x32_bf16 v[62:65], v[146:149], v[216:219], v[62:65]
	v_mfma_f32_16x16x32_bf16 v[58:61], v[164:167], v[216:219], v[58:61]
	v_mfma_f32_16x16x32_bf16 v[54:57], v[146:149], v[224:227], v[54:57]
	v_mfma_f32_16x16x32_bf16 v[46:49], v[164:167], v[224:227], v[46:49]
	v_mfma_f32_16x16x32_bf16 v[34:37], v[146:149], v[232:235], v[34:37]
	v_mfma_f32_16x16x32_bf16 v[26:29], v[164:167], v[232:235], v[26:29]
	v_mfma_f32_16x16x32_bf16 v[22:25], v[146:149], v[240:243], v[22:25]
	v_mfma_f32_16x16x32_bf16 v[14:17], v[164:167], v[240:243], v[14:17]
	v_mfma_f32_16x16x32_bf16 v[62:65], v[150:153], v[220:223], v[62:65]
	v_mfma_f32_16x16x32_bf16 v[58:61], v[168:171], v[220:223], v[58:61]
	v_mfma_f32_16x16x32_bf16 v[54:57], v[150:153], v[228:231], v[54:57]
	v_mfma_f32_16x16x32_bf16 v[46:49], v[168:171], v[228:231], v[46:49]
	v_mfma_f32_16x16x32_bf16 v[34:37], v[150:153], v[236:239], v[34:37]
	v_mfma_f32_16x16x32_bf16 v[26:29], v[168:171], v[236:239], v[26:29]
	v_mfma_f32_16x16x32_bf16 v[22:25], v[150:153], v[244:247], v[22:25]
	v_mfma_f32_16x16x32_bf16 v[14:17], v[168:171], v[244:247], v[14:17]
	s_setprio 0
	s_setprio 1
	v_mfma_f32_16x16x32_bf16 v[50:53], v[176:179], v[216:219], v[50:53]
	v_mfma_f32_16x16x32_bf16 v[42:45], v[184:187], v[216:219], v[42:45]
	v_mfma_f32_16x16x32_bf16 v[38:41], v[176:179], v[224:227], v[38:41]
	v_mfma_f32_16x16x32_bf16 v[30:33], v[184:187], v[224:227], v[30:33]
	v_mfma_f32_16x16x32_bf16 v[18:21], v[176:179], v[232:235], v[18:21]
	v_mfma_f32_16x16x32_bf16 v[10:13], v[184:187], v[232:235], v[10:13]
	v_mfma_f32_16x16x32_bf16 v[6:9], v[176:179], v[240:243], v[6:9]
	v_mfma_f32_16x16x32_bf16 v[2:5], v[184:187], v[240:243], v[2:5]
	v_mfma_f32_16x16x32_bf16 v[50:53], v[180:183], v[220:223], v[50:53]
	v_mfma_f32_16x16x32_bf16 v[42:45], v[212:215], v[220:223], v[42:45]
	v_mfma_f32_16x16x32_bf16 v[38:41], v[180:183], v[228:231], v[38:41]
	v_mfma_f32_16x16x32_bf16 v[30:33], v[212:215], v[228:231], v[30:33]
	v_mfma_f32_16x16x32_bf16 v[18:21], v[180:183], v[236:239], v[18:21]
	v_mfma_f32_16x16x32_bf16 v[10:13], v[212:215], v[236:239], v[10:13]
	v_mfma_f32_16x16x32_bf16 v[6:9], v[180:183], v[244:247], v[6:9]
	v_mfma_f32_16x16x32_bf16 v[2:5], v[212:215], v[244:247], v[2:5]
	s_setprio 0
	s_barrier
	s_add_i32 s52, s52, 2
	s_add_u32 s30, s30, 0x100
	s_addc_u32 s31, s31, 0
	s_add_u32 s50, s50, 0x100
	s_addc_u32 s51, s51, 0
	s_cmp_gt_u32 s52, 13
	s_cbranch_scc0 .LBB0_628
	s_and_b64 vcc, exec, s[8:9]
	s_cbranch_vccz .LBB0_631
	s_barrier

.LBB0_682:
	s_add_i32 s58, s38, 2
	s_add_u32 s59, s12, 0x80
	s_addc_u32 s39, s13, 0
	s_add_i32 s42, 0, 0x10000
	s_cmp_eq_u32 s95, s38
	s_cselect_b32 s39, s55, s39
	s_cselect_b32 s38, s54, s59
	s_cselect_b32 vcc_hi, s57, s41
	s_cselect_b32 vcc_lo, s56, s40
	s_add_i32 s43, 0, 0x14000
	v_add_u32_e32 v54, s42, v174
	v_add_u32_e32 v172, s43, v174
	ds_read_b128 v[38:41], v54
	ds_read_b128 v[46:49], v54 offset:1024
	ds_read_b128 v[50:53], v54 offset:2048
	ds_read_b128 v[54:57], v54 offset:3072
	ds_read_b128 v[164:167], v172
	ds_read_b128 v[168:171], v172 offset:1024
	ds_read_b128 v[178:181], v172 offset:2048
	ds_read_b128 v[182:185], v172 offset:3072
	v_lshl_add_u64 v[172:173], s[12:13], 0, v[152:153]
	s_add_i32 m0, s62, 0xc000
	ds_read_b128 v[212:215], v177
	ds_read_b128 v[216:219], v177 offset:1024
	ds_read_b128 v[220:223], v177 offset:2048
	ds_read_b128 v[224:227], v177 offset:3072
	ds_read_b128 v[228:231], v177 offset:4096
	ds_read_b128 v[232:235], v177 offset:5120
	ds_read_b128 v[236:239], v177 offset:6144
	ds_read_b128 v[240:243], v177 offset:7168
	global_load_lds_dwordx4 v[172:173], off
	v_lshl_add_u64 v[172:173], s[12:13], 0, v[154:155]
	s_add_i32 m0, s62, 0xe000
	s_nop 0
	global_load_lds_dwordx4 v[172:173], off
	s_waitcnt vmcnt(8) lgkmcnt(0)
	s_barrier
	s_setprio 1
	s_waitcnt lgkmcnt(0)
	v_mfma_f32_16x16x32_bf16 v[142:145], v[38:41], v[212:215], v[142:145]
	v_mfma_f32_16x16x32_bf16 v[138:141], v[50:53], v[212:215], v[138:141]
	v_mfma_f32_16x16x32_bf16 v[126:129], v[38:41], v[220:223], v[126:129]
	v_mfma_f32_16x16x32_bf16 v[122:125], v[50:53], v[220:223], v[122:125]
	v_mfma_f32_16x16x32_bf16 v[110:113], v[38:41], v[228:231], v[110:113]
	v_mfma_f32_16x16x32_bf16 v[106:109], v[50:53], v[228:231], v[106:109]
	v_mfma_f32_16x16x32_bf16 v[94:97], v[38:41], v[236:239], v[94:97]
	v_mfma_f32_16x16x32_bf16 v[90:93], v[50:53], v[236:239], v[90:93]
	v_mfma_f32_16x16x32_bf16 v[142:145], v[46:49], v[216:219], v[142:145]
	v_mfma_f32_16x16x32_bf16 v[138:141], v[54:57], v[216:219], v[138:141]
	v_mfma_f32_16x16x32_bf16 v[126:129], v[46:49], v[224:227], v[126:129]
	v_mfma_f32_16x16x32_bf16 v[122:125], v[54:57], v[224:227], v[122:125]
	v_mfma_f32_16x16x32_bf16 v[110:113], v[46:49], v[232:235], v[110:113]
	v_mfma_f32_16x16x32_bf16 v[106:109], v[54:57], v[232:235], v[106:109]
	v_mfma_f32_16x16x32_bf16 v[94:97], v[46:49], v[240:243], v[94:97]
	v_mfma_f32_16x16x32_bf16 v[90:93], v[54:57], v[240:243], v[90:93]
	s_setprio 0
	s_setprio 1
	v_mfma_f32_16x16x32_bf16 v[134:137], v[164:167], v[212:215], v[134:137]
	v_mfma_f32_16x16x32_bf16 v[130:133], v[178:181], v[212:215], v[130:133]
	v_mfma_f32_16x16x32_bf16 v[118:121], v[164:167], v[220:223], v[118:121]
	v_mfma_f32_16x16x32_bf16 v[114:117], v[178:181], v[220:223], v[114:117]
	v_mfma_f32_16x16x32_bf16 v[102:105], v[164:167], v[228:231], v[102:105]
	v_mfma_f32_16x16x32_bf16 v[98:101], v[178:181], v[228:231], v[98:101]
	v_mfma_f32_16x16x32_bf16 v[86:89], v[164:167], v[236:239], v[86:89]
	v_mfma_f32_16x16x32_bf16 v[82:85], v[178:181], v[236:239], v[82:85]
	v_mfma_f32_16x16x32_bf16 v[134:137], v[168:171], v[216:219], v[134:137]
	v_mfma_f32_16x16x32_bf16 v[130:133], v[182:185], v[216:219], v[130:133]
	v_mfma_f32_16x16x32_bf16 v[118:121], v[168:171], v[224:227], v[118:121]
	v_mfma_f32_16x16x32_bf16 v[114:117], v[182:185], v[224:227], v[114:117]
	v_mfma_f32_16x16x32_bf16 v[102:105], v[168:171], v[232:235], v[102:105]
	v_mfma_f32_16x16x32_bf16 v[98:101], v[182:185], v[232:235], v[98:101]
	v_mfma_f32_16x16x32_bf16 v[86:89], v[168:171], v[240:243], v[86:89]
	v_mfma_f32_16x16x32_bf16 v[82:85], v[182:185], v[240:243], v[82:85]
	s_setprio 0
	s_barrier
	s_add_i32 s42, s42, s61
	v_lshl_add_u64 v[172:173], vcc, 0, v[0:1]
	s_mov_b32 m0, s42
	ds_read_b128 v[212:215], v177 offset:16384
	ds_read_b128 v[216:219], v177 offset:17408
	ds_read_b128 v[220:223], v177 offset:18432
	ds_read_b128 v[224:227], v177 offset:19456
	ds_read_b128 v[228:231], v177 offset:20480
	ds_read_b128 v[232:235], v177 offset:21504
	ds_read_b128 v[236:239], v177 offset:22528
	ds_read_b128 v[240:243], v177 offset:23552
	global_load_lds_dwordx4 v[172:173], off
	s_add_i32 m0, s42, 0x2000
	v_lshl_add_u64 v[186:187], vcc, 0, v[150:151]
	s_add_u32 vcc_lo, vcc_lo, s7
	s_addc_u32 vcc_hi, vcc_hi, 0
	s_add_i32 s42, s43, s61
	global_load_lds_dwordx4 v[186:187], off
	v_lshl_add_u64 v[198:199], vcc, 0, v[0:1]
	s_mov_b32 m0, s42
	v_lshl_add_u64 v[244:245], vcc, 0, v[150:151]
	global_load_lds_dwordx4 v[198:199], off
	s_add_i32 m0, s42, 0x2000
	v_lshl_add_u64 v[246:247], s[38:39], 0, v[146:147]
	global_load_lds_dwordx4 v[244:245], off
	s_mov_b32 m0, s62
	v_lshl_add_u64 v[248:249], s[38:39], 0, v[148:149]
	global_load_lds_dwordx4 v[246:247], off
	s_mov_b32 m0, s63
	s_nop 0
	global_load_lds_dwordx4 v[248:249], off
	s_waitcnt vmcnt(8) lgkmcnt(0)
	s_barrier
	s_setprio 1
	s_waitcnt lgkmcnt(0)
	v_mfma_f32_16x16x32_bf16 v[78:81], v[38:41], v[212:215], v[78:81]
	v_mfma_f32_16x16x32_bf16 v[74:77], v[50:53], v[212:215], v[74:77]
	v_mfma_f32_16x16x32_bf16 v[62:65], v[38:41], v[220:223], v[62:65]
	v_mfma_f32_16x16x32_bf16 v[58:61], v[50:53], v[220:223], v[58:61]
	v_mfma_f32_16x16x32_bf16 v[30:33], v[38:41], v[228:231], v[30:33]
	v_mfma_f32_16x16x32_bf16 v[26:29], v[50:53], v[228:231], v[26:29]
	v_mfma_f32_16x16x32_bf16 v[14:17], v[38:41], v[236:239], v[14:17]
	v_mfma_f32_16x16x32_bf16 v[10:13], v[50:53], v[236:239], v[10:13]
	v_mfma_f32_16x16x32_bf16 v[78:81], v[46:49], v[216:219], v[78:81]
	v_mfma_f32_16x16x32_bf16 v[74:77], v[54:57], v[216:219], v[74:77]
	v_mfma_f32_16x16x32_bf16 v[62:65], v[46:49], v[224:227], v[62:65]
	v_mfma_f32_16x16x32_bf16 v[58:61], v[54:57], v[224:227], v[58:61]
	v_mfma_f32_16x16x32_bf16 v[30:33], v[46:49], v[232:235], v[30:33]
	v_mfma_f32_16x16x32_bf16 v[26:29], v[54:57], v[232:235], v[26:29]
	v_mfma_f32_16x16x32_bf16 v[14:17], v[46:49], v[240:243], v[14:17]
	v_mfma_f32_16x16x32_bf16 v[10:13], v[54:57], v[240:243], v[10:13]
	s_setprio 0
	s_setprio 1
	v_mfma_f32_16x16x32_bf16 v[42:45], v[164:167], v[220:223], v[42:45]
	v_mfma_f32_16x16x32_bf16 v[34:37], v[178:181], v[220:223], v[34:37]
	v_mfma_f32_16x16x32_bf16 v[22:25], v[164:167], v[228:231], v[22:25]
	v_mfma_f32_16x16x32_bf16 v[18:21], v[178:181], v[228:231], v[18:21]
	v_mfma_f32_16x16x32_bf16 v[6:9], v[164:167], v[236:239], v[6:9]
	v_mfma_f32_16x16x32_bf16 v[2:5], v[178:181], v[236:239], v[2:5]
	v_mfma_f32_16x16x32_bf16 v[38:41], v[164:167], v[212:215], v[70:73]
	v_mfma_f32_16x16x32_bf16 v[46:49], v[178:181], v[212:215], v[66:69]
	v_mfma_f32_16x16x32_bf16 v[42:45], v[168:171], v[224:227], v[42:45]
	v_mfma_f32_16x16x32_bf16 v[34:37], v[182:185], v[224:227], v[34:37]
	v_mfma_f32_16x16x32_bf16 v[22:25], v[168:171], v[232:235], v[22:25]
	v_mfma_f32_16x16x32_bf16 v[18:21], v[182:185], v[232:235], v[18:21]
	v_mfma_f32_16x16x32_bf16 v[6:9], v[168:171], v[240:243], v[6:9]
	v_mfma_f32_16x16x32_bf16 v[2:5], v[182:185], v[240:243], v[2:5]
	v_mfma_f32_16x16x32_bf16 v[38:41], v[168:171], v[216:219], v[38:41]
	v_mfma_f32_16x16x32_bf16 v[46:49], v[182:185], v[216:219], v[46:49]
	s_setprio 0
	s_barrier
	s_add_i32 s42, 0, 0x18000
	s_add_i32 s43, 0, 0x1c000
	v_add_u32_e32 v70, s42, v174
	v_add_u32_e32 v182, s43, v174
	ds_read_b128 v[50:53], v70
	ds_read_b128 v[54:57], v70 offset:1024
	ds_read_b128 v[66:69], v70 offset:2048
	ds_read_b128 v[70:73], v70 offset:3072
	ds_read_b128 v[164:167], v182
	ds_read_b128 v[168:171], v182 offset:1024
	ds_read_b128 v[178:181], v182 offset:2048
	ds_read_b128 v[182:185], v182 offset:3072
	s_add_u32 s38, s38, s26
	s_addc_u32 s39, s39, 0
	s_mov_b32 m0, s64
	v_lshl_add_u64 v[250:251], s[38:39], 0, v[146:147]
	ds_read_b128 v[212:215], v177 offset:32768
	ds_read_b128 v[216:219], v177 offset:33792
	ds_read_b128 v[220:223], v177 offset:34816
	ds_read_b128 v[224:227], v177 offset:35840
	ds_read_b128 v[228:231], v177 offset:36864
	ds_read_b128 v[232:235], v177 offset:37888
	ds_read_b128 v[236:239], v177 offset:38912
	ds_read_b128 v[240:243], v177 offset:39936
	global_load_lds_dwordx4 v[250:251], off
	v_lshl_add_u64 v[250:251], s[38:39], 0, v[148:149]
	s_mov_b32 m0, s65
	s_nop 0
	global_load_lds_dwordx4 v[250:251], off
	s_waitcnt vmcnt(8) lgkmcnt(0)
	s_barrier
	s_setprio 1
	s_waitcnt lgkmcnt(0)
	v_mfma_f32_16x16x32_bf16 v[142:145], v[50:53], v[212:215], v[142:145]
	v_mfma_f32_16x16x32_bf16 v[138:141], v[66:69], v[212:215], v[138:141]
	v_mfma_f32_16x16x32_bf16 v[126:129], v[50:53], v[220:223], v[126:129]
	v_mfma_f32_16x16x32_bf16 v[122:125], v[66:69], v[220:223], v[122:125]
	v_mfma_f32_16x16x32_bf16 v[110:113], v[50:53], v[228:231], v[110:113]
	v_mfma_f32_16x16x32_bf16 v[106:109], v[66:69], v[228:231], v[106:109]
	v_mfma_f32_16x16x32_bf16 v[94:97], v[50:53], v[236:239], v[94:97]
	v_mfma_f32_16x16x32_bf16 v[90:93], v[66:69], v[236:239], v[90:93]
	v_mfma_f32_16x16x32_bf16 v[142:145], v[54:57], v[216:219], v[142:145]
	v_mfma_f32_16x16x32_bf16 v[138:141], v[70:73], v[216:219], v[138:141]
	v_mfma_f32_16x16x32_bf16 v[126:129], v[54:57], v[224:227], v[126:129]
	v_mfma_f32_16x16x32_bf16 v[122:125], v[70:73], v[224:227], v[122:125]
	v_mfma_f32_16x16x32_bf16 v[110:113], v[54:57], v[232:235], v[110:113]
	v_mfma_f32_16x16x32_bf16 v[106:109], v[70:73], v[232:235], v[106:109]
	v_mfma_f32_16x16x32_bf16 v[94:97], v[54:57], v[240:243], v[94:97]
	v_mfma_f32_16x16x32_bf16 v[90:93], v[70:73], v[240:243], v[90:93]
	s_setprio 0
	s_setprio 1
	v_mfma_f32_16x16x32_bf16 v[134:137], v[164:167], v[212:215], v[134:137]
	v_mfma_f32_16x16x32_bf16 v[130:133], v[178:181], v[212:215], v[130:133]
	v_mfma_f32_16x16x32_bf16 v[118:121], v[164:167], v[220:223], v[118:121]
	v_mfma_f32_16x16x32_bf16 v[114:117], v[178:181], v[220:223], v[114:117]
	v_mfma_f32_16x16x32_bf16 v[102:105], v[164:167], v[228:231], v[102:105]
	v_mfma_f32_16x16x32_bf16 v[98:101], v[178:181], v[228:231], v[98:101]
	v_mfma_f32_16x16x32_bf16 v[86:89], v[164:167], v[236:239], v[86:89]
	v_mfma_f32_16x16x32_bf16 v[82:85], v[178:181], v[236:239], v[82:85]
	v_mfma_f32_16x16x32_bf16 v[134:137], v[168:171], v[216:219], v[134:137]
	v_mfma_f32_16x16x32_bf16 v[130:133], v[182:185], v[216:219], v[130:133]
	v_mfma_f32_16x16x32_bf16 v[118:121], v[168:171], v[224:227], v[118:121]
	v_mfma_f32_16x16x32_bf16 v[114:117], v[182:185], v[224:227], v[114:117]
	v_mfma_f32_16x16x32_bf16 v[102:105], v[168:171], v[232:235], v[102:105]
	v_mfma_f32_16x16x32_bf16 v[98:101], v[182:185], v[232:235], v[98:101]
	v_mfma_f32_16x16x32_bf16 v[86:89], v[168:171], v[240:243], v[86:89]
	v_mfma_f32_16x16x32_bf16 v[82:85], v[182:185], v[240:243], v[82:85]
	s_setprio 0
	s_barrier
	s_add_i32 s38, s42, s61
	v_lshl_add_u64 v[172:173], v[172:173], 0, s[20:21]
	s_mov_b32 m0, s38
	ds_read_b128 v[212:215], v177 offset:49152
	ds_read_b128 v[216:219], v177 offset:50176
	ds_read_b128 v[220:223], v177 offset:51200
	ds_read_b128 v[224:227], v177 offset:52224
	ds_read_b128 v[228:231], v177 offset:53248
	ds_read_b128 v[232:235], v177 offset:54272
	ds_read_b128 v[236:239], v177 offset:55296
	ds_read_b128 v[240:243], v177 offset:56320
	global_load_lds_dwordx4 v[172:173], off
	v_lshl_add_u64 v[172:173], v[186:187], 0, s[20:21]
	s_add_i32 m0, s38, 0x2000
	s_add_i32 s38, s43, s61
	global_load_lds_dwordx4 v[172:173], off
	v_lshl_add_u64 v[172:173], v[198:199], 0, s[20:21]
	s_mov_b32 m0, s38
	s_nop 0
	global_load_lds_dwordx4 v[172:173], off
	v_lshl_add_u64 v[172:173], v[244:245], 0, s[20:21]
	s_add_i32 m0, s38, 0x2000
	s_nop 0
	global_load_lds_dwordx4 v[172:173], off
	v_lshl_add_u64 v[172:173], v[246:247], 0, s[20:21]
	s_mov_b32 m0, s92
	s_nop 0
	global_load_lds_dwordx4 v[172:173], off
	v_lshl_add_u64 v[172:173], v[248:249], 0, s[20:21]
	s_mov_b32 m0, s93
	s_nop 0
	global_load_lds_dwordx4 v[172:173], off
	s_waitcnt vmcnt(8) lgkmcnt(0)
	s_barrier
	s_setprio 1
	s_waitcnt lgkmcnt(0)
	v_mfma_f32_16x16x32_bf16 v[78:81], v[50:53], v[212:215], v[78:81]
	v_mfma_f32_16x16x32_bf16 v[74:77], v[66:69], v[212:215], v[74:77]
	v_mfma_f32_16x16x32_bf16 v[62:65], v[50:53], v[220:223], v[62:65]
	v_mfma_f32_16x16x32_bf16 v[58:61], v[66:69], v[220:223], v[58:61]
	v_mfma_f32_16x16x32_bf16 v[30:33], v[50:53], v[228:231], v[30:33]
	v_mfma_f32_16x16x32_bf16 v[26:29], v[66:69], v[228:231], v[26:29]
	v_mfma_f32_16x16x32_bf16 v[14:17], v[50:53], v[236:239], v[14:17]
	v_mfma_f32_16x16x32_bf16 v[10:13], v[66:69], v[236:239], v[10:13]
	v_mfma_f32_16x16x32_bf16 v[78:81], v[54:57], v[216:219], v[78:81]
	v_mfma_f32_16x16x32_bf16 v[74:77], v[70:73], v[216:219], v[74:77]
	v_mfma_f32_16x16x32_bf16 v[62:65], v[54:57], v[224:227], v[62:65]
	v_mfma_f32_16x16x32_bf16 v[58:61], v[70:73], v[224:227], v[58:61]
	v_mfma_f32_16x16x32_bf16 v[30:33], v[54:57], v[232:235], v[30:33]
	v_mfma_f32_16x16x32_bf16 v[26:29], v[70:73], v[232:235], v[26:29]
	v_mfma_f32_16x16x32_bf16 v[14:17], v[54:57], v[240:243], v[14:17]
	v_mfma_f32_16x16x32_bf16 v[10:13], v[70:73], v[240:243], v[10:13]
	s_setprio 0
	s_setprio 1
	v_mfma_f32_16x16x32_bf16 v[38:41], v[164:167], v[212:215], v[38:41]
	v_mfma_f32_16x16x32_bf16 v[70:73], v[168:171], v[216:219], v[38:41]
	v_mfma_f32_16x16x32_bf16 v[38:41], v[178:181], v[212:215], v[46:49]
	v_mfma_f32_16x16x32_bf16 v[66:69], v[182:185], v[216:219], v[38:41]
	v_mfma_f32_16x16x32_bf16 v[38:41], v[164:167], v[220:223], v[42:45]
	v_mfma_f32_16x16x32_bf16 v[34:37], v[178:181], v[220:223], v[34:37]
	v_mfma_f32_16x16x32_bf16 v[22:25], v[164:167], v[228:231], v[22:25]
	v_mfma_f32_16x16x32_bf16 v[18:21], v[178:181], v[228:231], v[18:21]
	v_mfma_f32_16x16x32_bf16 v[6:9], v[164:167], v[236:239], v[6:9]
	v_mfma_f32_16x16x32_bf16 v[2:5], v[178:181], v[236:239], v[2:5]
	v_mfma_f32_16x16x32_bf16 v[42:45], v[168:171], v[224:227], v[38:41]
	v_mfma_f32_16x16x32_bf16 v[34:37], v[182:185], v[224:227], v[34:37]
	v_mfma_f32_16x16x32_bf16 v[22:25], v[168:171], v[232:235], v[22:25]
	v_mfma_f32_16x16x32_bf16 v[18:21], v[182:185], v[232:235], v[18:21]
	v_mfma_f32_16x16x32_bf16 v[6:9], v[168:171], v[240:243], v[6:9]
	v_mfma_f32_16x16x32_bf16 v[2:5], v[182:185], v[240:243], v[2:5]
	s_setprio 0
	s_barrier
	s_add_u32 s12, s12, 0x100
	s_addc_u32 s13, s13, 0
	s_add_u32 s40, s40, 0x100
	s_addc_u32 s41, s41, 0
	s_cmp_ge_u32 s58, s30
	s_mov_b32 s38, s58
	s_cbranch_scc0 .LBB0_682
	v_readlane_b32 s12, v254, 49
	v_readlane_b32 s13, v254, 50
	s_and_b64 vcc, exec, s[12:13]
	s_cbranch_vccz .LBB0_685
	s_barrier

.LBB0_812:
	s_add_u32 s38, s36, 0xfffc0080
	s_addc_u32 s39, s37, -1
	s_add_i32 s55, 0, 0x10000
	s_cmp_eq_u32 s54, 12
	s_cselect_b32 s41, s17, s39
	s_cselect_b32 s40, s50, s38
	v_add_u32_e32 v149, s55, v145
	s_cselect_b32 s39, s15, s53
	s_cselect_b32 s38, s51, s52
	s_add_i32 s58, 0, 0x14000
	ds_read_b128 v[140:143], v149
	ds_read_b128 v[150:153], v149 offset:1024
	ds_read_b128 v[164:167], v149 offset:2048
	ds_read_b128 v[168:171], v149 offset:3072
	v_add_u32_e32 v149, s58, v145
	ds_read_b128 v[176:179], v149
	ds_read_b128 v[180:183], v149 offset:1024
	ds_read_b128 v[184:187], v149 offset:2048
	ds_read_b128 v[212:215], v149 offset:3072
	v_lshl_add_u64 v[154:155], s[36:37], 0, v[136:137]
	s_add_i32 m0, s42, 0xc000
	ds_read_b128 v[216:219], v148
	ds_read_b128 v[220:223], v148 offset:1024
	ds_read_b128 v[224:227], v148 offset:2048
	ds_read_b128 v[228:231], v148 offset:3072
	ds_read_b128 v[232:235], v148 offset:4096
	ds_read_b128 v[236:239], v148 offset:5120
	ds_read_b128 v[240:243], v148 offset:6144
	ds_read_b128 v[244:247], v148 offset:7168
	global_load_lds_dwordx4 v[154:155], off
	v_lshl_add_u64 v[154:155], s[36:37], 0, v[138:139]
	s_add_i32 m0, s42, 0xe000
	s_nop 0
	global_load_lds_dwordx4 v[154:155], off
	s_waitcnt vmcnt(8) lgkmcnt(0)
	s_barrier
	s_setprio 1
	s_waitcnt lgkmcnt(0)
	v_mfma_f32_16x16x32_bf16 v[126:129], v[140:143], v[216:219], v[126:129]
	v_mfma_f32_16x16x32_bf16 v[118:121], v[164:167], v[216:219], v[118:121]
	v_mfma_f32_16x16x32_bf16 v[110:113], v[140:143], v[224:227], v[110:113]
	v_mfma_f32_16x16x32_bf16 v[102:105], v[164:167], v[224:227], v[102:105]
	v_mfma_f32_16x16x32_bf16 v[94:97], v[140:143], v[232:235], v[94:97]
	v_mfma_f32_16x16x32_bf16 v[86:89], v[164:167], v[232:235], v[86:89]
	v_mfma_f32_16x16x32_bf16 v[78:81], v[140:143], v[240:243], v[78:81]
	v_mfma_f32_16x16x32_bf16 v[70:73], v[164:167], v[240:243], v[70:73]
	v_mfma_f32_16x16x32_bf16 v[126:129], v[150:153], v[220:223], v[126:129]
	v_mfma_f32_16x16x32_bf16 v[118:121], v[168:171], v[220:223], v[118:121]
	v_mfma_f32_16x16x32_bf16 v[110:113], v[150:153], v[228:231], v[110:113]
	v_mfma_f32_16x16x32_bf16 v[102:105], v[168:171], v[228:231], v[102:105]
	v_mfma_f32_16x16x32_bf16 v[94:97], v[150:153], v[236:239], v[94:97]
	v_mfma_f32_16x16x32_bf16 v[86:89], v[168:171], v[236:239], v[86:89]
	v_mfma_f32_16x16x32_bf16 v[78:81], v[150:153], v[244:247], v[78:81]
	v_mfma_f32_16x16x32_bf16 v[70:73], v[168:171], v[244:247], v[70:73]
	s_setprio 0
	s_setprio 1
	v_mfma_f32_16x16x32_bf16 v[122:125], v[176:179], v[216:219], v[122:125]
	v_mfma_f32_16x16x32_bf16 v[114:117], v[184:187], v[216:219], v[114:117]
	v_mfma_f32_16x16x32_bf16 v[106:109], v[176:179], v[224:227], v[106:109]
	v_mfma_f32_16x16x32_bf16 v[98:101], v[184:187], v[224:227], v[98:101]
	v_mfma_f32_16x16x32_bf16 v[90:93], v[176:179], v[232:235], v[90:93]
	v_mfma_f32_16x16x32_bf16 v[82:85], v[184:187], v[232:235], v[82:85]
	v_mfma_f32_16x16x32_bf16 v[74:77], v[176:179], v[240:243], v[74:77]
	v_mfma_f32_16x16x32_bf16 v[66:69], v[184:187], v[240:243], v[66:69]
	v_mfma_f32_16x16x32_bf16 v[122:125], v[180:183], v[220:223], v[122:125]
	v_mfma_f32_16x16x32_bf16 v[114:117], v[212:215], v[220:223], v[114:117]
	v_mfma_f32_16x16x32_bf16 v[106:109], v[180:183], v[228:231], v[106:109]
	v_mfma_f32_16x16x32_bf16 v[98:101], v[212:215], v[228:231], v[98:101]
	v_mfma_f32_16x16x32_bf16 v[90:93], v[180:183], v[236:239], v[90:93]
	v_mfma_f32_16x16x32_bf16 v[82:85], v[212:215], v[236:239], v[82:85]
	v_mfma_f32_16x16x32_bf16 v[74:77], v[180:183], v[244:247], v[74:77]
	v_mfma_f32_16x16x32_bf16 v[66:69], v[212:215], v[244:247], v[66:69]
	s_setprio 0
	s_barrier
	s_add_i32 s55, s55, s7
	v_lshl_add_u64 v[154:155], s[38:39], 0, v[0:1]
	s_mov_b32 m0, s55
	ds_read_b128 v[216:219], v148 offset:16384
	ds_read_b128 v[220:223], v148 offset:17408
	ds_read_b128 v[224:227], v148 offset:18432
	ds_read_b128 v[228:231], v148 offset:19456
	ds_read_b128 v[232:235], v148 offset:20480
	ds_read_b128 v[236:239], v148 offset:21504
	ds_read_b128 v[240:243], v148 offset:22528
	ds_read_b128 v[244:247], v148 offset:23552
	global_load_lds_dwordx4 v[154:155], off
	s_add_i32 m0, s55, 0x2000
	s_add_u32 s56, s38, 0x40000
	v_lshl_add_u64 v[172:173], s[38:39], 0, v[134:135]
	s_addc_u32 s57, s39, 0
	s_add_i32 s55, s58, s7
	global_load_lds_dwordx4 v[172:173], off
	v_lshl_add_u64 v[248:249], s[56:57], 0, v[0:1]
	s_mov_b32 m0, s55
	v_lshl_add_u64 v[250:251], s[40:41], 0, v[132:133]
	global_load_lds_dwordx4 v[248:249], off
	v_lshl_add_u64 v[248:249], s[56:57], 0, v[134:135]
	s_add_i32 m0, s55, 0x2000
	s_nop 0
	global_load_lds_dwordx4 v[248:249], off
	v_lshl_add_u64 v[248:249], s[40:41], 0, v[130:131]
	s_mov_b32 m0, s42
	s_nop 0
	global_load_lds_dwordx4 v[248:249], off
	s_mov_b32 m0, s43
	s_nop 0
	global_load_lds_dwordx4 v[250:251], off
	s_waitcnt vmcnt(8) lgkmcnt(0)
	s_barrier
	s_setprio 1
	s_waitcnt lgkmcnt(0)
	v_mfma_f32_16x16x32_bf16 v[62:65], v[140:143], v[216:219], v[62:65]
	v_mfma_f32_16x16x32_bf16 v[54:57], v[164:167], v[216:219], v[54:57]
	v_mfma_f32_16x16x32_bf16 v[46:49], v[140:143], v[224:227], v[46:49]
	v_mfma_f32_16x16x32_bf16 v[38:41], v[164:167], v[224:227], v[38:41]
	v_mfma_f32_16x16x32_bf16 v[30:33], v[140:143], v[232:235], v[30:33]
	v_mfma_f32_16x16x32_bf16 v[22:25], v[164:167], v[232:235], v[22:25]
	v_mfma_f32_16x16x32_bf16 v[14:17], v[140:143], v[240:243], v[14:17]
	v_mfma_f32_16x16x32_bf16 v[6:9], v[164:167], v[240:243], v[6:9]
	v_mfma_f32_16x16x32_bf16 v[62:65], v[150:153], v[220:223], v[62:65]
	v_mfma_f32_16x16x32_bf16 v[54:57], v[168:171], v[220:223], v[54:57]
	v_mfma_f32_16x16x32_bf16 v[46:49], v[150:153], v[228:231], v[46:49]
	v_mfma_f32_16x16x32_bf16 v[38:41], v[168:171], v[228:231], v[38:41]
	v_mfma_f32_16x16x32_bf16 v[30:33], v[150:153], v[236:239], v[30:33]
	v_mfma_f32_16x16x32_bf16 v[22:25], v[168:171], v[236:239], v[22:25]
	v_mfma_f32_16x16x32_bf16 v[14:17], v[150:153], v[244:247], v[14:17]
	v_mfma_f32_16x16x32_bf16 v[6:9], v[168:171], v[244:247], v[6:9]
	s_setprio 0
	s_setprio 1
	v_mfma_f32_16x16x32_bf16 v[58:61], v[176:179], v[216:219], v[58:61]
	v_mfma_f32_16x16x32_bf16 v[50:53], v[184:187], v[216:219], v[50:53]
	v_mfma_f32_16x16x32_bf16 v[42:45], v[176:179], v[224:227], v[42:45]
	v_mfma_f32_16x16x32_bf16 v[34:37], v[184:187], v[224:227], v[34:37]
	v_mfma_f32_16x16x32_bf16 v[26:29], v[176:179], v[232:235], v[26:29]
	v_mfma_f32_16x16x32_bf16 v[18:21], v[184:187], v[232:235], v[18:21]
	v_mfma_f32_16x16x32_bf16 v[10:13], v[176:179], v[240:243], v[10:13]
	v_mfma_f32_16x16x32_bf16 v[2:5], v[184:187], v[240:243], v[2:5]
	v_mfma_f32_16x16x32_bf16 v[58:61], v[180:183], v[220:223], v[58:61]
	v_mfma_f32_16x16x32_bf16 v[50:53], v[212:215], v[220:223], v[50:53]
	v_mfma_f32_16x16x32_bf16 v[42:45], v[180:183], v[228:231], v[42:45]
	v_mfma_f32_16x16x32_bf16 v[34:37], v[212:215], v[228:231], v[34:37]
	v_mfma_f32_16x16x32_bf16 v[26:29], v[180:183], v[236:239], v[26:29]
	v_mfma_f32_16x16x32_bf16 v[18:21], v[212:215], v[236:239], v[18:21]
	v_mfma_f32_16x16x32_bf16 v[10:13], v[180:183], v[244:247], v[10:13]
	v_mfma_f32_16x16x32_bf16 v[2:5], v[212:215], v[244:247], v[2:5]
	s_setprio 0
	s_barrier
	s_add_i32 s55, 0, 0x18000
	v_add_u32_e32 v149, s55, v145
	s_add_i32 s56, 0, 0x1c000
	ds_read_b128 v[140:143], v149
	ds_read_b128 v[150:153], v149 offset:1024
	ds_read_b128 v[164:167], v149 offset:2048
	ds_read_b128 v[168:171], v149 offset:3072
	v_add_u32_e32 v149, s56, v145
	ds_read_b128 v[176:179], v149
	ds_read_b128 v[180:183], v149 offset:1024
	ds_read_b128 v[184:187], v149 offset:2048
	ds_read_b128 v[212:215], v149 offset:3072
	s_add_u32 s40, s40, 0x40000
	s_addc_u32 s41, s41, 0
	s_mov_b32 m0, s44
	v_lshl_add_u64 v[198:199], s[40:41], 0, v[130:131]
	ds_read_b128 v[216:219], v148 offset:32768
	ds_read_b128 v[220:223], v148 offset:33792
	ds_read_b128 v[224:227], v148 offset:34816
	ds_read_b128 v[228:231], v148 offset:35840
	ds_read_b128 v[232:235], v148 offset:36864
	ds_read_b128 v[236:239], v148 offset:37888
	ds_read_b128 v[240:243], v148 offset:38912
	ds_read_b128 v[244:247], v148 offset:39936
	global_load_lds_dwordx4 v[198:199], off
	v_lshl_add_u64 v[198:199], s[40:41], 0, v[132:133]
	s_mov_b32 m0, s45
	s_nop 0
	global_load_lds_dwordx4 v[198:199], off
	s_waitcnt vmcnt(8) lgkmcnt(0)
	s_barrier
	s_setprio 1
	s_waitcnt lgkmcnt(0)
	v_mfma_f32_16x16x32_bf16 v[126:129], v[140:143], v[216:219], v[126:129]
	v_mfma_f32_16x16x32_bf16 v[118:121], v[164:167], v[216:219], v[118:121]
	v_mfma_f32_16x16x32_bf16 v[110:113], v[140:143], v[224:227], v[110:113]
	v_mfma_f32_16x16x32_bf16 v[102:105], v[164:167], v[224:227], v[102:105]
	v_mfma_f32_16x16x32_bf16 v[94:97], v[140:143], v[232:235], v[94:97]
	v_mfma_f32_16x16x32_bf16 v[86:89], v[164:167], v[232:235], v[86:89]
	v_mfma_f32_16x16x32_bf16 v[78:81], v[140:143], v[240:243], v[78:81]
	v_mfma_f32_16x16x32_bf16 v[70:73], v[164:167], v[240:243], v[70:73]
	v_mfma_f32_16x16x32_bf16 v[126:129], v[150:153], v[220:223], v[126:129]
	v_mfma_f32_16x16x32_bf16 v[118:121], v[168:171], v[220:223], v[118:121]
	v_mfma_f32_16x16x32_bf16 v[110:113], v[150:153], v[228:231], v[110:113]
	v_mfma_f32_16x16x32_bf16 v[102:105], v[168:171], v[228:231], v[102:105]
	v_mfma_f32_16x16x32_bf16 v[94:97], v[150:153], v[236:239], v[94:97]
	v_mfma_f32_16x16x32_bf16 v[86:89], v[168:171], v[236:239], v[86:89]
	v_mfma_f32_16x16x32_bf16 v[78:81], v[150:153], v[244:247], v[78:81]
	v_mfma_f32_16x16x32_bf16 v[70:73], v[168:171], v[244:247], v[70:73]
	s_setprio 0
	s_setprio 1
	v_mfma_f32_16x16x32_bf16 v[122:125], v[176:179], v[216:219], v[122:125]
	v_mfma_f32_16x16x32_bf16 v[114:117], v[184:187], v[216:219], v[114:117]
	v_mfma_f32_16x16x32_bf16 v[106:109], v[176:179], v[224:227], v[106:109]
	v_mfma_f32_16x16x32_bf16 v[98:101], v[184:187], v[224:227], v[98:101]
	v_mfma_f32_16x16x32_bf16 v[90:93], v[176:179], v[232:235], v[90:93]
	v_mfma_f32_16x16x32_bf16 v[82:85], v[184:187], v[232:235], v[82:85]
	v_mfma_f32_16x16x32_bf16 v[74:77], v[176:179], v[240:243], v[74:77]
	v_mfma_f32_16x16x32_bf16 v[66:69], v[184:187], v[240:243], v[66:69]
	v_mfma_f32_16x16x32_bf16 v[122:125], v[180:183], v[220:223], v[122:125]
	v_mfma_f32_16x16x32_bf16 v[114:117], v[212:215], v[220:223], v[114:117]
	v_mfma_f32_16x16x32_bf16 v[106:109], v[180:183], v[228:231], v[106:109]
	v_mfma_f32_16x16x32_bf16 v[98:101], v[212:215], v[228:231], v[98:101]
	v_mfma_f32_16x16x32_bf16 v[90:93], v[180:183], v[236:239], v[90:93]
	v_mfma_f32_16x16x32_bf16 v[82:85], v[212:215], v[236:239], v[82:85]
	v_mfma_f32_16x16x32_bf16 v[74:77], v[180:183], v[244:247], v[74:77]
	v_mfma_f32_16x16x32_bf16 v[66:69], v[212:215], v[244:247], v[66:69]
	s_setprio 0
	s_barrier
	s_add_i32 s40, s55, s7
	v_lshl_add_u64 v[154:155], v[154:155], 0, s[20:21]
	s_mov_b32 m0, s40
	ds_read_b128 v[216:219], v148 offset:49152
	ds_read_b128 v[220:223], v148 offset:50176
	ds_read_b128 v[224:227], v148 offset:51200
	ds_read_b128 v[228:231], v148 offset:52224
	ds_read_b128 v[232:235], v148 offset:53248
	ds_read_b128 v[236:239], v148 offset:54272
	ds_read_b128 v[240:243], v148 offset:55296
	ds_read_b128 v[244:247], v148 offset:56320
	global_load_lds_dwordx4 v[154:155], off
	s_add_i32 m0, s40, 0x2000
	s_add_u32 s38, s38, 0x40080
	v_lshl_add_u64 v[154:155], v[172:173], 0, s[20:21]
	s_addc_u32 s39, s39, 0
	s_add_i32 s40, s56, s7
	global_load_lds_dwordx4 v[154:155], off
	v_lshl_add_u64 v[154:155], s[38:39], 0, v[0:1]
	s_mov_b32 m0, s40
	s_nop 0
	global_load_lds_dwordx4 v[154:155], off
	v_lshl_add_u64 v[154:155], s[38:39], 0, v[134:135]
	s_add_i32 m0, s40, 0x2000
	s_nop 0
	global_load_lds_dwordx4 v[154:155], off
	v_lshl_add_u64 v[154:155], v[248:249], 0, s[20:21]
	s_mov_b32 m0, s46
	s_nop 0
	global_load_lds_dwordx4 v[154:155], off
	v_lshl_add_u64 v[154:155], v[250:251], 0, s[20:21]
	s_mov_b32 m0, s47
	s_nop 0
	global_load_lds_dwordx4 v[154:155], off
	s_waitcnt vmcnt(8) lgkmcnt(0)
	s_barrier
	s_setprio 1
	s_waitcnt lgkmcnt(0)
	v_mfma_f32_16x16x32_bf16 v[62:65], v[140:143], v[216:219], v[62:65]
	v_mfma_f32_16x16x32_bf16 v[54:57], v[164:167], v[216:219], v[54:57]
	v_mfma_f32_16x16x32_bf16 v[46:49], v[140:143], v[224:227], v[46:49]
	v_mfma_f32_16x16x32_bf16 v[38:41], v[164:167], v[224:227], v[38:41]
	v_mfma_f32_16x16x32_bf16 v[30:33], v[140:143], v[232:235], v[30:33]
	v_mfma_f32_16x16x32_bf16 v[22:25], v[164:167], v[232:235], v[22:25]
	v_mfma_f32_16x16x32_bf16 v[14:17], v[140:143], v[240:243], v[14:17]
	v_mfma_f32_16x16x32_bf16 v[6:9], v[164:167], v[240:243], v[6:9]
	v_mfma_f32_16x16x32_bf16 v[62:65], v[150:153], v[220:223], v[62:65]
	v_mfma_f32_16x16x32_bf16 v[54:57], v[168:171], v[220:223], v[54:57]
	v_mfma_f32_16x16x32_bf16 v[46:49], v[150:153], v[228:231], v[46:49]
	v_mfma_f32_16x16x32_bf16 v[38:41], v[168:171], v[228:231], v[38:41]
	v_mfma_f32_16x16x32_bf16 v[30:33], v[150:153], v[236:239], v[30:33]
	v_mfma_f32_16x16x32_bf16 v[22:25], v[168:171], v[236:239], v[22:25]
	v_mfma_f32_16x16x32_bf16 v[14:17], v[150:153], v[244:247], v[14:17]
	v_mfma_f32_16x16x32_bf16 v[6:9], v[168:171], v[244:247], v[6:9]
	s_setprio 0
	s_setprio 1
	v_mfma_f32_16x16x32_bf16 v[58:61], v[176:179], v[216:219], v[58:61]
	v_mfma_f32_16x16x32_bf16 v[50:53], v[184:187], v[216:219], v[50:53]
	v_mfma_f32_16x16x32_bf16 v[42:45], v[176:179], v[224:227], v[42:45]
	v_mfma_f32_16x16x32_bf16 v[34:37], v[184:187], v[224:227], v[34:37]
	v_mfma_f32_16x16x32_bf16 v[26:29], v[176:179], v[232:235], v[26:29]
	v_mfma_f32_16x16x32_bf16 v[18:21], v[184:187], v[232:235], v[18:21]
	v_mfma_f32_16x16x32_bf16 v[10:13], v[176:179], v[240:243], v[10:13]
	v_mfma_f32_16x16x32_bf16 v[2:5], v[184:187], v[240:243], v[2:5]
	v_mfma_f32_16x16x32_bf16 v[58:61], v[180:183], v[220:223], v[58:61]
	v_mfma_f32_16x16x32_bf16 v[50:53], v[212:215], v[220:223], v[50:53]
	v_mfma_f32_16x16x32_bf16 v[42:45], v[180:183], v[228:231], v[42:45]
	v_mfma_f32_16x16x32_bf16 v[34:37], v[212:215], v[228:231], v[34:37]
	v_mfma_f32_16x16x32_bf16 v[26:29], v[180:183], v[236:239], v[26:29]
	v_mfma_f32_16x16x32_bf16 v[18:21], v[212:215], v[236:239], v[18:21]
	v_mfma_f32_16x16x32_bf16 v[10:13], v[180:183], v[244:247], v[10:13]
	v_mfma_f32_16x16x32_bf16 v[2:5], v[212:215], v[244:247], v[2:5]
	s_setprio 0
	s_barrier
	s_add_i32 s54, s54, 2
	s_add_u32 s36, s36, 0x100
	s_addc_u32 s37, s37, 0
	s_add_u32 s52, s52, 0x100
	s_addc_u32 s53, s53, 0
	s_cmp_gt_u32 s54, 13
	s_cbranch_scc0 .LBB0_812
	s_and_b64 vcc, exec, s[12:13]
	s_cbranch_vccz .LBB0_815
	s_barrier
